# v14 + dsa_in EpiBf16<3> second bias batch hoisted into free v[236:243] (loaded with the first batch, waits removed)
# baseline (speedup 1.0000x reference)
;     __device__ __forceinline__ void operator()(const f32x4 (&acc)[2][2][4][2], const Unit& u, int wr, int wc, int fr, int fq) const {
;     ...
;         if (MODE == 3) {
; #pragma unroll
;             for (int i = 0; i < 8; ++i) { const f32x4 t = *(const f32x4*)(p0 + (size_t)(row0 + (i >> 2) * HALF + (i & 3) * 16) * 16 + 4 * fq); rs[i] = (t.x + t.y) + (t.z + t.w); }
; #pragma unroll
;             for (int i = 0; i < 8; ++i) { float t = rs[i]; t += __shfl_xor(t, 16); t += __shfl_xor(t, 32); rs[i] = __builtin_amdgcn_rsqf(t * (1.f / 1024.f) + 1e-6f); }
;         }
;     ...
;             if (MODE == 3) { b0 = *(const f32x4*)(p1 + (size_t)(u.pm >> 4) * ldc + c); b1 = *(const f32x4*)(p1 + (size_t)(u.pm >> 4) * ldc + c + 4); }
.LBB0_514:
	v_lshl_add_u32 v186, s34, 8, v155
	v_ashrrev_i32_e32 v187, 31, v186
	v_or_b32_e32 v184, 16, v186
	v_lshlrev_b64 v[128:129], 6, v[186:187]
	v_ashrrev_i32_e32 v185, 31, v184
	v_lshl_add_u64 v[128:129], v[144:145], 0, v[128:129]
	v_lshlrev_b64 v[130:131], 6, v[184:185]
	v_lshl_add_u64 v[130:131], v[144:145], 0, v[130:131]
	global_load_dwordx4 v[190:193], v[128:129], off
	global_load_dwordx4 v[194:197], v[130:131], off
	v_or_b32_e32 v180, 32, v186
	v_ashrrev_i32_e32 v181, 31, v180
	v_or_b32_e32 v176, 48, v186
	v_lshlrev_b64 v[128:129], 6, v[180:181]
	v_ashrrev_i32_e32 v177, 31, v176
	v_lshl_add_u64 v[128:129], v[144:145], 0, v[128:129]
	v_lshlrev_b64 v[130:131], 6, v[176:177]
	v_lshl_add_u64 v[130:131], v[144:145], 0, v[130:131]
	global_load_dwordx4 v[198:201], v[128:129], off
	global_load_dwordx4 v[202:205], v[130:131], off
	v_add_u32_e32 v170, 0x80, v186
	v_ashrrev_i32_e32 v171, 31, v170
	v_add_u32_e32 v168, 0x90, v186
	v_lshlrev_b64 v[128:129], 6, v[170:171]
	v_ashrrev_i32_e32 v169, 31, v168
	v_lshl_add_u64 v[128:129], v[144:145], 0, v[128:129]
	v_lshlrev_b64 v[130:131], 6, v[168:169]
	v_lshl_add_u64 v[130:131], v[144:145], 0, v[130:131]
	global_load_dwordx4 v[208:211], v[128:129], off
	global_load_dwordx4 v[212:215], v[130:131], off
	v_add_u32_e32 v164, 0xa0, v186
	v_ashrrev_i32_e32 v165, 31, v164
	v_lshlrev_b64 v[128:129], 6, v[164:165]
	v_add_u32_e32 v160, 0xb0, v186
	v_lshl_add_u64 v[128:129], v[144:145], 0, v[128:129]
	v_ashrrev_i32_e32 v161, 31, v160
	global_load_dwordx4 v[216:219], v[128:129], off
	v_lshlrev_b64 v[128:129], 6, v[160:161]
	v_lshl_add_u64 v[128:129], v[144:145], 0, v[128:129]
	global_load_dwordx4 v[220:223], v[128:129], off
	s_ashr_i32 s4, s34, 4
	s_mul_hi_i32 s5, s4, 0x2400
	s_mulk_i32 s4, 0x2400
	v_lshl_or_b32 v224, s54, 8, v159
	s_add_u32 s4, s8, s4
	v_ashrrev_i32_e32 v225, 31, v224
	s_addc_u32 s5, s9, s5
	v_lshl_add_u64 v[174:175], v[224:225], 2, s[4:5]
	global_load_dwordx4 v[128:131], v[174:175], off offset:16
	global_load_dwordx4 v[132:135], v[174:175], off
	global_load_dwordx4 v[236:239], v[174:175], off offset:512
	global_load_dwordx4 v[240:243], v[174:175], off offset:528
	v_and_b32_e32 v166, 64, v183
	v_xor_b32_e32 v154, 16, v183
	v_add_u32_e32 v166, 64, v166
	v_cmp_lt_i32_e32 vcc, v154, v166
	v_xor_b32_e32 v177, 32, v183
	v_readlane_b32 s4, v248, 61
	v_cndmask_b32_e32 v154, v183, v154, vcc
	v_lshlrev_b32_e32 v154, 2, v154
	v_cmp_lt_i32_e32 vcc, v177, v166
	v_readlane_b32 s5, v248, 62
	s_waitcnt vmcnt(0)
	v_mov_b32_e32 v226, v191
	v_mov_b32_e32 v227, v192
	v_mov_b32_e32 v191, v193
	v_pk_add_f32 v[190:191], v[226:227], v[190:191]
	v_mov_b32_e32 v192, v195
	v_add_f32_e32 v156, v190, v191
	ds_bpermute_b32 v172, v154, v156
	v_mov_b32_e32 v193, v196
	v_mov_b32_e32 v195, v197
	v_pk_add_f32 v[190:191], v[192:193], v[194:195]
	v_cndmask_b32_e32 v166, v183, v177, vcc
	v_add_f32_e32 v158, v190, v191
	v_lshlrev_b32_e32 v177, 2, v166
	s_waitcnt lgkmcnt(0)
	v_add_f32_e32 v156, v156, v172
	ds_bpermute_b32 v166, v177, v156
	ds_bpermute_b32 v172, v154, v158
	v_mov_b32_e32 v196, v199
	v_mov_b32_e32 v197, v200
	v_mov_b32_e32 v199, v201
	v_pk_add_f32 v[192:193], v[196:197], v[198:199]
	s_waitcnt lgkmcnt(1)
	v_add_f32_e32 v156, v156, v166
	v_add_f32_e32 v161, v192, v193
	ds_bpermute_b32 v166, v154, v161
	s_waitcnt lgkmcnt(1)
	v_add_f32_e32 v158, v158, v172
	ds_bpermute_b32 v172, v177, v158
	v_mov_b32_e32 v200, v203
	v_mov_b32_e32 v201, v204
	v_mov_b32_e32 v203, v205
	v_fmamk_f32 v156, v156, 0x3a800000, v188
	v_mov_b32_e32 v204, v209
	v_mov_b32_e32 v205, v210
	v_mov_b32_e32 v209, v211
	v_pk_add_f32 v[194:195], v[200:201], v[202:203]
	v_rsq_f32_e32 v182, v156
	s_waitcnt lgkmcnt(1)
	v_add_f32_e32 v156, v161, v166
	v_pk_add_f32 v[196:197], v[204:205], v[208:209]
	v_add_f32_e32 v162, v194, v195
	ds_bpermute_b32 v161, v177, v156
	s_waitcnt lgkmcnt(1)
	v_add_f32_e32 v158, v158, v172
	v_add_f32_e32 v165, v196, v197
	v_fmamk_f32 v158, v158, 0x3a800000, v188
	ds_bpermute_b32 v166, v154, v162
	v_rsq_f32_e32 v178, v158
	ds_bpermute_b32 v158, v154, v165
	v_mov_b32_e32 v210, v213
	v_mov_b32_e32 v211, v214
	v_mov_b32_e32 v213, v215
	s_waitcnt lgkmcnt(2)
	v_add_f32_e32 v156, v156, v161
	v_pk_add_f32 v[198:199], v[210:211], v[212:213]
	v_fmamk_f32 v156, v156, 0x3a800000, v188
	s_waitcnt lgkmcnt(1)
	v_add_f32_e32 v161, v162, v166
	v_add_f32_e32 v169, v198, v199
	ds_bpermute_b32 v162, v177, v161
	v_rsq_f32_e32 v172, v156
	s_waitcnt lgkmcnt(1)
	v_add_f32_e32 v156, v165, v158
	ds_bpermute_b32 v158, v177, v156
	ds_bpermute_b32 v165, v154, v169
	v_mov_b32_e32 v214, v217
	v_mov_b32_e32 v215, v218
	v_mov_b32_e32 v217, v219
	v_pk_add_f32 v[200:201], v[214:215], v[216:217]
	s_waitcnt lgkmcnt(2)
	v_add_f32_e32 v161, v161, v162
	v_mov_b32_e32 v218, v221
	v_mov_b32_e32 v219, v222
	v_add_f32_e32 v171, v200, v201
	v_mov_b32_e32 v221, v223
	v_fmamk_f32 v161, v161, 0x3a800000, v188
	s_waitcnt lgkmcnt(1)
	v_add_f32_e32 v156, v156, v158
	s_waitcnt lgkmcnt(0)
	v_add_f32_e32 v158, v169, v165
	v_pk_add_f32 v[190:191], v[218:219], v[220:221]
	v_rsq_f32_e32 v166, v161
	ds_bpermute_b32 v161, v177, v158
	ds_bpermute_b32 v165, v154, v171
	v_add_f32_e32 v181, v190, v191
	ds_bpermute_b32 v154, v154, v181
	v_mov_b64_e32 v[190:191], s[4:5]
	v_fmamk_f32 v156, v156, 0x3a800000, v188
	v_mad_i64_i32 v[186:187], s[4:5], v186, s52, v[190:191]
	v_lshlrev_b64 v[192:193], 1, v[224:225]
	v_rsq_f32_e32 v162, v156
	s_waitcnt lgkmcnt(2)
	v_add_f32_e32 v156, v158, v161
	s_waitcnt lgkmcnt(1)
; __device__ __forceinline__ unsigned cvt_pk_bf16(float lo, float hi) { unsigned r; asm volatile("v_cvt_pk_bf16_f32 %0, %1, %2" : "=v"(r) : "v"(lo), "v"(hi)); return r; }
; __device__ __forceinline__ float sigmoidf_(float x) { return __builtin_amdgcn_rcpf(1.f + __expf(-x)); }
;     __device__ __forceinline__ void operator()(const f32x4 (&acc)[2][2][4][2], const Unit& u, int wr, int wc, int fr, int fq) const {
;     ...
;             for (int ai = 0; ai < 2; ++ai)
; #pragma unroll
;                 for (int m = 0; m < 4; ++m) { bf16_t* rowp = O + (size_t)(row0 + ai * HALF + m * 16) * ldc + c;
;                     f32x4 v0, v1;
;                     if (MODE == 3) { const float rstd = rs[ai * 4 + m]; v0 = acc[ai][bj][m][0] * rstd + b0; v1 = acc[ai][bj][m][1] * rstd + b1; }
;                     else { v0 = acc[ai][bj][m][0] + b0; v1 = acc[ai][bj][m][1] + b1; }
;                     if (MODE == 1 || MODE == 2) {
; #pragma unroll
;                         for (int e = 0; e < 4; ++e) {
;                             if (kind == 1) { v0[e] = 2.f * sigmoidf_(2.f * v0[e]) - 1.f; v1[e] = 2.f * sigmoidf_(2.f * v1[e]) - 1.f; }
;                             else if (kind == 2) { v0[e] = sigmoidf_(v0[e]); v1[e] = sigmoidf_(v1[e]); }
;                             else if (kind == 3) { v0[e] = 0.60653066f * sigmoidf_(v0[e]); v1[e] = 0.60653066f * sigmoidf_(v1[e]); }
;                         }
;                     }
;                     u32x4 w; w.x = cvt_pk_bf16(v0[0], v0[1]); w.y = cvt_pk_bf16(v0[2], v0[3]); w.z = cvt_pk_bf16(v1[0], v1[1]); w.w = cvt_pk_bf16(v1[2], v1[3]);
;                     *(u32x4*)rowp = w; }
	v_add_f32_e32 v161, v171, v165
	v_lshl_add_u64 v[186:187], v[186:187], 0, v[192:193]
	v_pk_fma_f32 v[126:127], v[126:127], v[182:183], v[134:135] op_sel_hi:[1,0,1]
	v_pk_fma_f32 v[124:125], v[124:125], v[182:183], v[132:133] op_sel_hi:[1,0,1]
	v_pk_fma_f32 v[194:195], v[122:123], v[182:183], v[130:131] op_sel_hi:[1,0,1]
	v_pk_fma_f32 v[122:123], v[120:121], v[182:183], v[128:129] op_sel_hi:[1,0,1]
	v_cvt_pk_bf16_f32 v120, v124, v125
	v_cvt_pk_bf16_f32 v121, v126, v127
	ds_bpermute_b32 v165, v177, v161
	v_cvt_pk_bf16_f32 v122, v122, v123
	v_cvt_pk_bf16_f32 v123, v194, v195
	global_store_dwordx4 v[186:187], v[120:123], off
	s_waitcnt lgkmcnt(1)
	v_add_f32_e32 v154, v181, v154
	v_pk_fma_f32 v[118:119], v[118:119], v[178:179], v[134:135] op_sel_hi:[1,0,1]
	v_mad_i64_i32 v[120:121], s[4:5], v184, s52, v[190:191]
	v_lshl_add_u64 v[120:121], v[120:121], 0, v[192:193]
	v_pk_fma_f32 v[116:117], v[116:117], v[178:179], v[132:133] op_sel_hi:[1,0,1]
	v_pk_fma_f32 v[122:123], v[114:115], v[178:179], v[130:131] op_sel_hi:[1,0,1]
	v_pk_fma_f32 v[114:115], v[112:113], v[178:179], v[128:129] op_sel_hi:[1,0,1]
	v_cvt_pk_bf16_f32 v112, v116, v117
	v_cvt_pk_bf16_f32 v113, v118, v119
	ds_bpermute_b32 v169, v177, v154
	v_cvt_pk_bf16_f32 v114, v114, v115
	v_cvt_pk_bf16_f32 v115, v122, v123
	global_store_dwordx4 v[120:121], v[112:115], off
	v_pk_fma_f32 v[110:111], v[110:111], v[172:173], v[134:135] op_sel_hi:[1,0,1]
	v_pk_fma_f32 v[108:109], v[108:109], v[172:173], v[132:133] op_sel_hi:[1,0,1]
	v_mad_i64_i32 v[112:113], s[4:5], v180, s52, v[190:191]
	v_lshl_add_u64 v[112:113], v[112:113], 0, v[192:193]
	v_pk_fma_f32 v[114:115], v[106:107], v[172:173], v[130:131] op_sel_hi:[1,0,1]
	v_pk_fma_f32 v[106:107], v[104:105], v[172:173], v[128:129] op_sel_hi:[1,0,1]
	v_cvt_pk_bf16_f32 v104, v108, v109
	v_cvt_pk_bf16_f32 v105, v110, v111
	v_fmamk_f32 v156, v156, 0x3a800000, v188
	v_cvt_pk_bf16_f32 v106, v106, v107
	v_cvt_pk_bf16_f32 v107, v114, v115
	global_store_dwordx4 v[112:113], v[104:107], off
	v_rsq_f32_e32 v158, v156
	s_waitcnt lgkmcnt(1)
	v_add_f32_e32 v156, v161, v165
	v_mad_i64_i32 v[104:105], s[4:5], v176, s52, v[190:191]
	v_lshl_add_u64 v[104:105], v[104:105], 0, v[192:193]
	v_pk_fma_f32 v[102:103], v[102:103], v[166:167], v[134:135] op_sel_hi:[1,0,1]
	v_pk_fma_f32 v[100:101], v[100:101], v[166:167], v[132:133] op_sel_hi:[1,0,1]
	v_pk_fma_f32 v[106:107], v[98:99], v[166:167], v[130:131] op_sel_hi:[1,0,1]
	v_pk_fma_f32 v[98:99], v[96:97], v[166:167], v[128:129] op_sel_hi:[1,0,1]
	v_cvt_pk_bf16_f32 v96, v100, v101
	v_cvt_pk_bf16_f32 v97, v102, v103
	v_fmamk_f32 v156, v156, 0x3a800000, v188
	v_cvt_pk_bf16_f32 v98, v98, v99
	v_cvt_pk_bf16_f32 v99, v106, v107
	global_store_dwordx4 v[104:105], v[96:99], off
	v_rsq_f32_e32 v156, v156
	s_waitcnt lgkmcnt(0)
; template <class Epi, class Sched, bool ALIGN_EPI = false, bool SP2 = false>
; __device__ __forceinline__ void gemm_phase(PG8_LAS unsigned char* lds, const Gemm g, const Sched& S, const Epi& E) {
;     ...
;         if constexpr (ALIGN_EPI) { if (wr == 0) PG8_BAR; }
;         if constexpr (!Epi::AFTER_DRAIN) { E(acc, cur, wr, wc, fr, fq); S.done(cur); }
;         if (!has_next) break;
; #pragma unroll
;     __device__ __forceinline__ void operator()(const f32x4 (&acc)[2][2][4][2], const Unit& u, int wr, int wc, int fr, int fq) const {
;     ...
;         for (int bj = 0; bj < 2; ++bj) {
;             const int c = col0 + bj * HALF;
;             f32x4 b0 = (f32x4){0.f, 0.f, 0.f, 0.f}, b1 = b0; int kind = 0;
;             if (MODE == 1) { kind = (c >= 3072 && c < 3136) ? 1 : ((c >= 3200) ? 2 : 0); }
;             if (MODE == 3) { b0 = *(const f32x4*)(p1 + (size_t)(u.pm >> 4) * ldc + c); b1 = *(const f32x4*)(p1 + (size_t)(u.pm >> 4) * ldc + c + 4); }
;             if (MODE == 2) { if (c < 1024) { kind = 3; b0 = *(const f32x4*)(p0 + c); b1 = *(const f32x4*)(p0 + c + 4); } else { kind = 2; b0 = *(const f32x4*)(p1 + c - 1024); b1 = *(const f32x4*)(p1 + c - 1024 + 4); } }
; #pragma unroll
;             for (int ai = 0; ai < 2; ++ai)
; #pragma unroll
;                 for (int m = 0; m < 4; ++m) { bf16_t* rowp = O + (size_t)(row0 + ai * HALF + m * 16) * ldc + c;
;                     f32x4 v0, v1;
;                     if (MODE == 3) { const float rstd = rs[ai * 4 + m]; v0 = acc[ai][bj][m][0] * rstd + b0; v1 = acc[ai][bj][m][1] * rstd + b1; }
;                     else { v0 = acc[ai][bj][m][0] + b0; v1 = acc[ai][bj][m][1] + b1; }
;                     if (MODE == 1 || MODE == 2) {
; #pragma unroll
;                         for (int e = 0; e < 4; ++e) {
;                             if (kind == 1) { v0[e] = 2.f * sigmoidf_(2.f * v0[e]) - 1.f; v1[e] = 2.f * sigmoidf_(2.f * v1[e]) - 1.f; }
;                             else if (kind == 2) { v0[e] = sigmoidf_(v0[e]); v1[e] = sigmoidf_(v1[e]); }
;                             else if (kind == 3) { v0[e] = 0.60653066f * sigmoidf_(v0[e]); v1[e] = 0.60653066f * sigmoidf_(v1[e]); }
;                         }
;                     }
;                     u32x4 w; w.x = cvt_pk_bf16(v0[0], v0[1]); w.y = cvt_pk_bf16(v0[2], v0[3]); w.z = cvt_pk_bf16(v1[0], v1[1]); w.w = cvt_pk_bf16(v1[2], v1[3]);
;                     *(u32x4*)rowp = w; }
	v_add_f32_e32 v154, v154, v169
	v_mad_i64_i32 v[96:97], s[4:5], v170, s52, v[190:191]
	v_lshl_add_u64 v[96:97], v[96:97], 0, v[192:193]
	v_pk_fma_f32 v[94:95], v[94:95], v[162:163], v[134:135] op_sel_hi:[1,0,1]
	v_pk_fma_f32 v[92:93], v[92:93], v[162:163], v[132:133] op_sel_hi:[1,0,1]
	v_pk_fma_f32 v[98:99], v[90:91], v[162:163], v[130:131] op_sel_hi:[1,0,1]
	v_pk_fma_f32 v[90:91], v[88:89], v[162:163], v[128:129] op_sel_hi:[1,0,1]
	v_cvt_pk_bf16_f32 v88, v92, v93
	v_cvt_pk_bf16_f32 v89, v94, v95
	v_fmamk_f32 v154, v154, 0x3a800000, v188
	v_cvt_pk_bf16_f32 v90, v90, v91
	v_cvt_pk_bf16_f32 v91, v98, v99
	global_store_dwordx4 v[96:97], v[88:91], off
	v_rsq_f32_e32 v154, v154
	v_pk_fma_f32 v[86:87], v[86:87], v[158:159], v[134:135] op_sel_hi:[1,0,1]
	v_mad_i64_i32 v[88:89], s[4:5], v168, s52, v[190:191]
	v_lshl_add_u64 v[88:89], v[88:89], 0, v[192:193]
	v_pk_fma_f32 v[84:85], v[84:85], v[158:159], v[132:133] op_sel_hi:[1,0,1]
	v_pk_fma_f32 v[90:91], v[82:83], v[158:159], v[130:131] op_sel_hi:[1,0,1]
	v_pk_fma_f32 v[82:83], v[80:81], v[158:159], v[128:129] op_sel_hi:[1,0,1]
	v_cvt_pk_bf16_f32 v80, v84, v85
	v_cvt_pk_bf16_f32 v81, v86, v87
	v_pk_fma_f32 v[78:79], v[78:79], v[156:157], v[134:135] op_sel_hi:[1,0,1]
	v_cvt_pk_bf16_f32 v82, v82, v83
	v_cvt_pk_bf16_f32 v83, v90, v91
	global_store_dwordx4 v[88:89], v[80:83], off
	v_pk_fma_f32 v[76:77], v[76:77], v[156:157], v[132:133] op_sel_hi:[1,0,1]
	v_pk_fma_f32 v[70:71], v[70:71], v[154:155], v[134:135] op_sel_hi:[1,0,1]
	v_mad_i64_i32 v[80:81], s[4:5], v164, s52, v[190:191]
	v_lshl_add_u64 v[80:81], v[80:81], 0, v[192:193]
	v_pk_fma_f32 v[82:83], v[74:75], v[156:157], v[130:131] op_sel_hi:[1,0,1]
	v_pk_fma_f32 v[74:75], v[72:73], v[156:157], v[128:129] op_sel_hi:[1,0,1]
	v_cvt_pk_bf16_f32 v72, v76, v77
	v_cvt_pk_bf16_f32 v73, v78, v79
	v_pk_fma_f32 v[68:69], v[68:69], v[154:155], v[132:133] op_sel_hi:[1,0,1]
	v_cvt_pk_bf16_f32 v74, v74, v75
	v_cvt_pk_bf16_f32 v75, v82, v83
	global_store_dwordx4 v[80:81], v[72:75], off
	s_and_b64 vcc, exec, s[2:3]
	s_mov_b64 s[2:3], -1
	v_mad_i64_i32 v[72:73], s[4:5], v160, s52, v[190:191]
	v_lshl_add_u64 v[72:73], v[72:73], 0, v[192:193]
	v_pk_fma_f32 v[74:75], v[66:67], v[154:155], v[130:131] op_sel_hi:[1,0,1]
	v_pk_fma_f32 v[66:67], v[64:65], v[154:155], v[128:129] op_sel_hi:[1,0,1]
	v_cvt_pk_bf16_f32 v64, v68, v69
	v_cvt_pk_bf16_f32 v65, v70, v71
	s_nop 0
	v_cvt_pk_bf16_f32 v66, v66, v67
	v_cvt_pk_bf16_f32 v67, v74, v75
	global_store_dwordx4 v[72:73], v[64:67], off
	s_nop 0
	v_pk_fma_f32 v[62:63], v[62:63], v[182:183], v[238:239] op_sel_hi:[1,0,1]
	v_pk_fma_f32 v[60:61], v[60:61], v[182:183], v[236:237] op_sel_hi:[1,0,1]
	v_pk_fma_f32 v[74:75], v[58:59], v[182:183], v[242:243] op_sel_hi:[1,0,1]
	v_pk_fma_f32 v[58:59], v[56:57], v[182:183], v[240:241] op_sel_hi:[1,0,1]
	v_cvt_pk_bf16_f32 v56, v60, v61
	v_cvt_pk_bf16_f32 v57, v62, v63
	v_pk_fma_f32 v[54:55], v[54:55], v[178:179], v[238:239] op_sel_hi:[1,0,1]
	v_cvt_pk_bf16_f32 v58, v58, v59
	v_cvt_pk_bf16_f32 v59, v74, v75
	global_store_dwordx4 v[186:187], v[56:59], off offset:256
	v_pk_fma_f32 v[52:53], v[52:53], v[178:179], v[236:237] op_sel_hi:[1,0,1]
	v_pk_fma_f32 v[46:47], v[46:47], v[172:173], v[238:239] op_sel_hi:[1,0,1]
	v_pk_fma_f32 v[56:57], v[50:51], v[178:179], v[242:243] op_sel_hi:[1,0,1]
	v_pk_fma_f32 v[50:51], v[48:49], v[178:179], v[240:241] op_sel_hi:[1,0,1]
	v_cvt_pk_bf16_f32 v48, v52, v53
	v_cvt_pk_bf16_f32 v49, v54, v55
	v_pk_fma_f32 v[44:45], v[44:45], v[172:173], v[236:237] op_sel_hi:[1,0,1]
	v_cvt_pk_bf16_f32 v50, v50, v51
	v_cvt_pk_bf16_f32 v51, v56, v57
	global_store_dwordx4 v[120:121], v[48:51], off offset:256
	v_pk_fma_f32 v[38:39], v[38:39], v[166:167], v[238:239] op_sel_hi:[1,0,1]
	v_pk_fma_f32 v[36:37], v[36:37], v[166:167], v[236:237] op_sel_hi:[1,0,1]
	v_pk_fma_f32 v[48:49], v[42:43], v[172:173], v[242:243] op_sel_hi:[1,0,1]
	v_pk_fma_f32 v[42:43], v[40:41], v[172:173], v[240:241] op_sel_hi:[1,0,1]
	v_cvt_pk_bf16_f32 v40, v44, v45
	v_cvt_pk_bf16_f32 v41, v46, v47
	v_pk_fma_f32 v[30:31], v[30:31], v[162:163], v[238:239] op_sel_hi:[1,0,1]
	v_cvt_pk_bf16_f32 v42, v42, v43
	v_cvt_pk_bf16_f32 v43, v48, v49
	global_store_dwordx4 v[112:113], v[40:43], off offset:256
	v_pk_fma_f32 v[28:29], v[28:29], v[162:163], v[236:237] op_sel_hi:[1,0,1]
	v_pk_fma_f32 v[22:23], v[22:23], v[158:159], v[238:239] op_sel_hi:[1,0,1]
	v_pk_fma_f32 v[40:41], v[34:35], v[166:167], v[242:243] op_sel_hi:[1,0,1]
	v_pk_fma_f32 v[34:35], v[32:33], v[166:167], v[240:241] op_sel_hi:[1,0,1]
	v_cvt_pk_bf16_f32 v32, v36, v37
	v_cvt_pk_bf16_f32 v33, v38, v39
	v_pk_fma_f32 v[20:21], v[20:21], v[158:159], v[236:237] op_sel_hi:[1,0,1]
	v_cvt_pk_bf16_f32 v34, v34, v35
	v_cvt_pk_bf16_f32 v35, v40, v41
	global_store_dwordx4 v[104:105], v[32:35], off offset:256
	v_pk_fma_f32 v[14:15], v[14:15], v[156:157], v[238:239] op_sel_hi:[1,0,1]
	v_pk_fma_f32 v[12:13], v[12:13], v[156:157], v[236:237] op_sel_hi:[1,0,1]
	v_pk_fma_f32 v[32:33], v[26:27], v[162:163], v[242:243] op_sel_hi:[1,0,1]
	v_pk_fma_f32 v[26:27], v[24:25], v[162:163], v[240:241] op_sel_hi:[1,0,1]
	v_cvt_pk_bf16_f32 v24, v28, v29
	v_cvt_pk_bf16_f32 v25, v30, v31
	v_pk_fma_f32 v[6:7], v[6:7], v[154:155], v[238:239] op_sel_hi:[1,0,1]
	v_cvt_pk_bf16_f32 v26, v26, v27
	v_cvt_pk_bf16_f32 v27, v32, v33
	global_store_dwordx4 v[96:97], v[24:27], off offset:256
	v_pk_fma_f32 v[4:5], v[4:5], v[154:155], v[236:237] op_sel_hi:[1,0,1]
	s_nop 0
	v_pk_fma_f32 v[24:25], v[18:19], v[158:159], v[242:243] op_sel_hi:[1,0,1]
	v_pk_fma_f32 v[18:19], v[16:17], v[158:159], v[240:241] op_sel_hi:[1,0,1]
	v_cvt_pk_bf16_f32 v16, v20, v21
	v_cvt_pk_bf16_f32 v17, v22, v23
	s_nop 0
	v_cvt_pk_bf16_f32 v18, v18, v19
	v_cvt_pk_bf16_f32 v19, v24, v25
	global_store_dwordx4 v[88:89], v[16:19], off offset:256
	s_nop 1
	v_pk_fma_f32 v[16:17], v[10:11], v[156:157], v[242:243] op_sel_hi:[1,0,1]
	v_pk_fma_f32 v[10:11], v[8:9], v[156:157], v[240:241] op_sel_hi:[1,0,1]
	v_cvt_pk_bf16_f32 v8, v12, v13
	v_cvt_pk_bf16_f32 v9, v14, v15
	s_nop 0
	v_cvt_pk_bf16_f32 v10, v10, v11
	v_cvt_pk_bf16_f32 v11, v16, v17
	global_store_dwordx4 v[80:81], v[8:11], off offset:256
	s_nop 1
	v_pk_fma_f32 v[8:9], v[2:3], v[154:155], v[242:243] op_sel_hi:[1,0,1]
	v_pk_fma_f32 v[2:3], v[0:1], v[154:155], v[240:241] op_sel_hi:[1,0,1]
	v_cvt_pk_bf16_f32 v0, v4, v5
	v_cvt_pk_bf16_f32 v1, v6, v7
	s_nop 0
	v_cvt_pk_bf16_f32 v2, v2, v3
	v_cvt_pk_bf16_f32 v3, v8, v9
	global_store_dwordx4 v[72:73], v[0:3], off offset:256
	s_cbranch_vccnz .LBB0_504
	s_andn2_b64 vcc, exec, s[20:21]
	s_cbranch_vccnz .LBB0_503
	s_barrier
	s_branch .LBB0_503
